# ret+mamba scan units: end-of-unit barrier removed (V^T/SDEC images written after the first barrier)
# speedup vs baseline: 1.0119x; 1.0039x over previous
; #define RT_DECODE(u, b_, h_, vs_, ck_, smp_, row0_, len_) do { if ((u) < np) { b_ = cb >> 5; h_ = (cb >> 3) & 3; vs_ = cb & 7; ck_ = (u); smp_ = false; row0_ = b_ * TP + 64 * ck_; len_ = ck_ < 32 ? 64 : 16; } \
;         else { const int it_ = (cb % 256) + ((u) - np) * G; b_ = it_ >> 5; h_ = (it_ >> 3) & 3; vs_ = it_ & 7; ck_ = 0; smp_ = true; row0_ = RP + 8 * b_; len_ = 8; } } while (0)
; __device__ __forceinline__ void ret_block(ArgsP a_, unsigned char* smem) { const ArgsP a = a_;
;     ...
;     for (int uu = 0; uu < ntot_; ++uu) { const int u = uu < np ? uu : np + (uu - np) % nsmp; const int un_ = uu + 1 < np ? uu + 1 : np + (uu + 1 - np) % nsmp;
;         int b, h, vs, ck, row0, len; bool sample; RT_DECODE(u, b, h, vs, ck, sample, row0, len);
;         const bool first = sample || ck == 0, last = sample || ck == 32;
;     ...
;         __syncthreads();
.LBB0_232:
	s_add_i32 s34, s85, s86
	s_cmp_eq_u32 s34, 0
	s_mov_b32 s34, s86
	v_readlane_b32 s67, v254, 58
	s_cbranch_scc1 .LBB0_306

; __device__ __forceinline__ void ret_block(ArgsP a_, unsigned char* smem) { const ArgsP a = a_;
;     ...
;         const float lgam = __logf(1.f - exp2f(-5.f - (float)h));
;         if (first) state_load<256, 64>(S, AIN(3) + (((size_t)b * 4 + h) * 256) * 512 + vs * 64, 512, wid, fr, fq, !sample);
; #pragma unroll
;         for (int e = 0; e < 4; ++e) { const int idx = tid + 512 * e, i = idx >> 5, cc = idx & 31; *(u32x4*)(QA + i * LQ + 8 * cc) = qpre[e]; *(u32x4*)(KB + i * LQ + 8 * cc) = kpre[e]; }
;         *(u32x4*)(VT + vv * LJ + 8 * jg) = (u32x4){(unsigned)vpre[0] | ((unsigned)vpre[1] << 16), (unsigned)vpre[2] | ((unsigned)vpre[3] << 16), (unsigned)vpre[4] | ((unsigned)vpre[5] << 16), (unsigned)vpre[6] | ((unsigned)vpre[7] << 16)};
;         if (tid < 64) { GI[tid] = (float)((tid + 1 < len) ? tid + 1 : len) * lgam; DECJ[tid] = tid < len ? __expf((float)(len - 1 - tid) * lgam) : 0.f; }
.LBB0_259:
	v_cvt_f32_ubyte0_e32 v16, s91
	v_sub_f32_e32 v16, 0xc0a00000, v16
	s_mov_b32 s64, 0xc2fc0000
	v_cmp_gt_f32_e32 vcc, s64, v16
	v_mov_b32_e32 v18, 0x42800000
	s_and_b64 s[64:65], vcc, exec
	v_cndmask_b32_e32 v18, 0, v18, vcc
	v_add_f32_e32 v16, v16, v18
	v_exp_f32_e32 v16, v16
	s_cselect_b32 s64, 0xffffffc0, 0
	ds_write_b128 v102, v[0:3]
	ds_write_b128 v102, v[4:7] offset:33792
	ds_write_b128 v104, v[8:11]
	ds_write_b128 v104, v[12:15] offset:33792
	ds_write_b128 v106, v[20:23]
	ds_write_b128 v106, v[24:27] offset:33792
	ds_write_b128 v108, v[28:31]
	ds_write_b128 v108, v[32:35] offset:33792
	v_ldexp_f32 v16, v16, s64
	v_sub_f32_e32 v16, 1.0, v16
	v_cmp_gt_f32_e32 vcc, s31, v16
	s_and_b64 s[64:65], vcc, exec
	s_cselect_b32 s64, 32, 0
	v_ldexp_f32 v16, v16, s64
	v_log_f32_e32 v16, v16
	s_nop 0
	v_mul_f32_e32 v18, 0x3f317217, v16
	v_fma_f32 v18, v16, s36, -v18
	v_fmac_f32_e32 v18, 0x3377d1cf, v16
	v_fmac_f32_e32 v18, 0x3f317217, v16
	v_cmp_lt_f32_e64 s[64:65], |v16|, s37
	s_nop 1
	v_cndmask_b32_e64 v16, v16, v18, s[64:65]
	v_cndmask_b32_e32 v18, 0, v191, vcc
	v_sub_f32_e32 v16, v16, v18
	s_and_saveexec_b64 s[64:65], s[40:41]
	s_cbranch_execz .LBB0_261
	v_min_i32_e32 v18, s89, v119
	v_cvt_f32_i32_e32 v18, v18
	v_cmp_gt_i32_e32 vcc, s89, v97
	v_mul_f32_e32 v18, v16, v18
	ds_write_b32 v120, v18
	v_add_u32_e32 v18, s89, v121
	v_cvt_f32_i32_e32 v18, v18
	v_mul_f32_e32 v18, v16, v18
	v_mul_f32_e32 v18, 0x3fb8aa3b, v18
	v_exp_f32_e32 v18, v18
	s_nop 0
	v_cndmask_b32_e32 v18, 0, v18, vcc
	ds_write_b32 v122, v18

; __device__ __forceinline__ unsigned cvt_pk_bf16(float lo, float hi) { unsigned r; asm("v_cvt_pk_bf16_f32 %0, %1, %2" : "=v"(r) : "v"(lo), "v"(hi)); return r; }
; template <int DK, int DV, bool SEPQ> ...
;     ...
;         for (int vt = 0; vt < NVT; ++vt) { const f32x4 s = S[ct][vt]; u32x2 w; w.x = cvt_pk_bf16(s[0], s[1]); w.y = cvt_pk_bf16(s[2], s[3]);
;             *(u32x2*)(ST + (16 * vt + fr) * LQ + 16 * (wid * NCTW + ct) + 4 * fq) = w; }
;     __syncthreads();
; __device__ __forceinline__ void ret_block(ArgsP a_, unsigned char* smem) { const ArgsP a = a_;
;     ...
;         if (tid < 256) SDEC[tid] = __expf((float)len * lgam);
;         __syncthreads();
;         if (uu + 1 < ntot_) RT_LOAD(un_);
.LBB0_263:
	s_waitcnt vmcnt(0)
	v_cvt_pk_bf16_f32 v0, v40, v41
	v_cvt_pk_bf16_f32 v1, v42, v43
	v_cvt_pk_bf16_f32 v2, v56, v57
	v_cvt_pk_bf16_f32 v3, v58, v59
	ds_write2_b64 v143, v[0:1], v[2:3] offset1:4
	v_cvt_pk_bf16_f32 v4, v44, v45
	v_cvt_pk_bf16_f32 v5, v46, v47
	v_cvt_pk_bf16_f32 v6, v60, v61
	v_cvt_pk_bf16_f32 v7, v62, v63
	v_add_u32_e32 v9, 0x2000, v143
	ds_write2_b64 v9, v[4:5], v[6:7] offset0:32 offset1:36
	v_cvt_pk_bf16_f32 v0, v48, v49
	v_cvt_pk_bf16_f32 v1, v50, v51
	v_cvt_pk_bf16_f32 v2, v64, v65
	v_cvt_pk_bf16_f32 v3, v66, v67
	v_add_u32_e32 v8, 0x4000, v143
	ds_write2_b64 v8, v[0:1], v[2:3] offset0:64 offset1:68
	v_cvt_pk_bf16_f32 v4, v52, v53
	v_cvt_pk_bf16_f32 v5, v54, v55
	v_cvt_pk_bf16_f32 v6, v68, v69
	v_cvt_pk_bf16_f32 v7, v70, v71
	v_add_u32_e32 v9, 0x6000, v143
	ds_write2_b64 v9, v[4:5], v[6:7] offset0:96 offset1:100
	s_waitcnt vmcnt(0) lgkmcnt(0)
	s_barrier
	ds_write_b128 v118, v[36:39]
	s_and_saveexec_b64 s[64:65], s[42:43]
	s_cbranch_execz .Lret_sdec_skip
	v_cvt_f32_u32_e32 v18, s89
	v_mul_f32_e32 v16, v16, v18
	v_mul_f32_e32 v16, 0x3fb8aa3b, v16
	v_exp_f32_e32 v16, v16
	ds_write_b32 v123, v16
.Lret_sdec_skip:
	s_or_b64 exec, exec, s[64:65]
	s_cmp_ge_i32 s86, s79
	s_cbranch_scc1 .LBB0_269
	s_cmp_ge_i32 s92, s77
	s_mov_b64 s[64:65], -1
	s_cbranch_scc0 .LBB0_266
	s_sub_i32 s64, s92, s77
	s_mul_i32 s64, s64, s13
	s_add_i32 s70, s64, s78
	s_ashr_i32 s64, s70, 2
	s_and_b32 s64, s64, -8
	s_add_i32 s67, s64, 0x4080
	s_mov_b64 s[64:65], 0

; #define MB_DECODE(u, b_, hd_, ck_, smp_, row0_, len_) do { if ((u) < np) { b_ = cb >> 5; hd_ = cb & 31; ck_ = (u); smp_ = false; row0_ = b_ * TP + 64 * ck_; len_ = ck_ < 32 ? 64 : 16; } \
;         else { const int it_ = (cb % 256) + ((u) - np) * G; b_ = it_ >> 5; hd_ = it_ & 31; ck_ = 0; smp_ = true; row0_ = RP + 8 * b_; len_ = 8; } } while (0)
; __device__ __forceinline__ void mamba_block(ArgsP a_, unsigned char* smem) { const ArgsP a = a_;
;     ...
;     for (int uu = 0; uu < ntot_; ++uu) { const int u = uu < np ? uu : np + (uu - np) % nsmp; const int un_ = uu + 1 < np ? uu + 1 : np + (uu + 1 - np) % nsmp;
;         int b, hd, ck, row0, len; bool sample; MB_DECODE(u, b, hd, ck, sample, row0, len);
;         const bool first = sample || ck == 0, last = sample || ck == 32;
;     ...
;         __syncthreads();
.LBB0_323:
	s_add_i32 s22, s68, s69
	s_cmp_eq_u32 s22, 0
	s_mov_b32 s34, s69
	s_cbranch_scc1 .LBB0_376

; __device__ __forceinline__ unsigned cvt_pk_bf16(float lo, float hi) { unsigned r; asm("v_cvt_pk_bf16_f32 %0, %1, %2" : "=v"(r) : "v"(lo), "v"(hi)); return r; }
; __device__ __forceinline__ float bf2f(bf16_t b) { return __uint_as_float(((unsigned)b) << 16); }
; template <int DK, int DV, bool SEPQ> ...
;     ...
;         for (int vt = 0; vt < NVT; ++vt) { const f32x4 s = S[ct][vt]; u32x2 w; w.x = cvt_pk_bf16(s[0], s[1]); w.y = cvt_pk_bf16(s[2], s[3]);
;             *(u32x2*)(ST + (16 * vt + fr) * LQ + 16 * (wid * NCTW + ct) + 4 * fq) = w; }
;     __syncthreads();
; __device__ __forceinline__ void mamba_block(ArgsP a_, unsigned char* smem) { const ArgsP a = a_;
;     ...
;             const float glast = __shfl(x, 63); GI[j] = x; DTV[j] = dt; W2[j] = dt * __expf(glast - x); const float ed = __expf(glast); SDEC[2 * j] = ed; SDEC[2 * j + 1] = ed; }
;         __syncthreads();
;         { unsigned w1[4], w2[4];
; #pragma unroll
;           for (int e = 0; e < 4; ++e) { const int j = 8 * jg + 2 * e; const float x0 = bf2f(xpre[2 * e]), x1 = bf2f(xpre[2 * e + 1]);
;               w1[e] = cvt_pk_bf16(x0 * DTV[j], x1 * DTV[j + 1]); w2[e] = cvt_pk_bf16(x0 * W2[j], x1 * W2[j + 1]); }
;           *(u32x4*)(VT + vv * LJ + 8 * jg) = (u32x4){w1[0], w1[1], w1[2], w1[3]}; *(u32x4*)(VT2 + vv * LJ + 8 * jg) = (u32x4){w2[0], w2[1], w2[2], w2[3]}; }
;         { const int cp = tid & 63, jq = tid >> 6;
;           unsigned lo[4], hi[4];
; #pragma unroll
;           for (int e = 0; e < 4; ++e) { const int j = 8 * jq + 2 * e; const unsigned w0 = *(const unsigned*)(KB + j * LQ + 2 * cp), w1 = *(const unsigned*)(KB + (j + 1) * LQ + 2 * cp);
;               lo[e] = (w0 & 0xffffu) | (w1 << 16); hi[e] = (w0 >> 16) | (w1 & 0xffff0000u); }
;           *(u32x4*)(KT + (2 * cp) * LJ + 8 * jq) = (u32x4){lo[0], lo[1], lo[2], lo[3]}; *(u32x4*)(KT + (2 * cp + 1) * LJ + 8 * jq) = (u32x4){hi[0], hi[1], hi[2], hi[3]}; }
.LBB0_348:
	s_or_b64 exec, exec, s[74:75]
	s_waitcnt vmcnt(0)
	v_cvt_pk_bf16_f32 v36, v20, v21
	v_cvt_pk_bf16_f32 v37, v22, v23
	ds_write_b64 v109, v[36:37]
	v_cvt_pk_bf16_f32 v36, v24, v25
	v_cvt_pk_bf16_f32 v37, v26, v27
	ds_write_b64 v109, v[36:37] offset:4352
	v_cvt_pk_bf16_f32 v36, v28, v29
	v_cvt_pk_bf16_f32 v37, v30, v31
	ds_write_b64 v109, v[36:37] offset:8704
	v_cvt_pk_bf16_f32 v36, v32, v33
	v_cvt_pk_bf16_f32 v37, v34, v35
	ds_write_b64 v109, v[36:37] offset:13056
	s_waitcnt vmcnt(0) lgkmcnt(0)
	s_barrier
	s_mov_b64 s[74:75], exec
	v_cmp_gt_u32_e32 vcc, 64, v186
	s_and_b64 exec, exec, vcc
	s_cbranch_execz .Lmb_sdec_skip
	ds_write_b64 v108, v[18:19]
.Lmb_sdec_skip:
	s_mov_b64 exec, s[74:75]
	ds_read_b64 v[220:221], v75
	ds_read_b64 v[222:223], v87
	ds_read_b64 v[224:225], v89
	ds_read_b64 v[226:227], v91
	ds_read_b64 v[228:229], v93
	ds_read_b64 v[230:231], v95
	ds_read_b64 v[232:233], v97
	ds_read_b64 v[234:235], v99
	v_lshlrev_b32_e32 v16, 16, v115
	v_lshlrev_b32_e32 v37, 16, v116
	v_lshlrev_b32_e32 v38, 16, v120
	v_lshlrev_b32_e32 v39, 16, v119
	s_waitcnt lgkmcnt(7)
	v_mul_f32_e32 v18, v220, v16
	v_mul_f32_e32 v19, v221, v37
	v_cvt_pk_bf16_f32 v36, v18, v19
	v_lshlrev_b32_e32 v43, 16, v122
	s_mov_b32 s22, 0xffff0000
	s_cmp_ge_i32 s69, s63
	s_waitcnt lgkmcnt(6)
	v_mul_f32_e32 v16, v222, v16
	v_mul_f32_e32 v18, v223, v37
	v_cvt_pk_bf16_f32 v40, v16, v18
	v_lshlrev_b32_e32 v16, 16, v117
	s_waitcnt lgkmcnt(5)
	v_mul_f32_e32 v18, v224, v16
	v_mul_f32_e32 v19, v225, v38
	v_cvt_pk_bf16_f32 v37, v18, v19
	s_waitcnt lgkmcnt(4)
	v_mul_f32_e32 v16, v226, v16
	v_mul_f32_e32 v18, v227, v38
	v_cvt_pk_bf16_f32 v41, v16, v18
	v_lshlrev_b32_e32 v16, 16, v118
	s_waitcnt lgkmcnt(3)
	v_mul_f32_e32 v18, v228, v16
	v_mul_f32_e32 v19, v229, v39
	v_cvt_pk_bf16_f32 v38, v18, v19
	s_waitcnt lgkmcnt(2)
	v_mul_f32_e32 v16, v230, v16
	v_mul_f32_e32 v18, v231, v39
	v_cvt_pk_bf16_f32 v42, v16, v18
	v_lshlrev_b32_e32 v16, 16, v121
	s_waitcnt lgkmcnt(1)
	v_mul_f32_e32 v18, v232, v16
	v_mul_f32_e32 v19, v233, v43
	v_cvt_pk_bf16_f32 v39, v18, v19
	s_waitcnt lgkmcnt(0)
	v_mul_f32_e32 v16, v234, v16
	v_mul_f32_e32 v18, v235, v43
	v_cvt_pk_bf16_f32 v43, v16, v18
	ds_write_b128 v79, v[36:39] offset:53248
	ds_write_b128 v79, v[40:43] offset:62464
	ds_read_b32 v236, v100 offset:17408
	ds_read_b32 v237, v101 offset:17680
	ds_read_b32 v238, v102 offset:17408
	ds_read_b32 v239, v103 offset:17680
	ds_read_b32 v240, v104 offset:17408
	ds_read_b32 v241, v105 offset:17680
	ds_read_b32 v242, v106 offset:17408
	ds_read_b32 v243, v107 offset:17680
	s_waitcnt lgkmcnt(7)
	v_and_b32_e32 v19, 0xffff, v236
	v_lshrrev_b32_e32 v16, 16, v236
	s_waitcnt lgkmcnt(6)
	v_lshl_or_b32 v36, v237, 16, v19
	v_and_or_b32 v40, v237, s22, v16
	s_waitcnt lgkmcnt(5)
	v_and_b32_e32 v19, 0xffff, v238
	v_lshrrev_b32_e32 v16, 16, v238
	s_waitcnt lgkmcnt(4)
	v_lshl_or_b32 v37, v239, 16, v19
	v_and_or_b32 v41, v239, s22, v16
	s_waitcnt lgkmcnt(3)
	v_and_b32_e32 v19, 0xffff, v240
	v_lshrrev_b32_e32 v16, 16, v240
	s_waitcnt lgkmcnt(2)
	v_lshl_or_b32 v38, v241, 16, v19
	v_and_or_b32 v42, v241, s22, v16
	s_waitcnt lgkmcnt(1)
	v_and_b32_e32 v19, 0xffff, v242
	s_waitcnt lgkmcnt(0)
	v_lshl_or_b32 v39, v243, 16, v19
	v_lshrrev_b32_e32 v16, 16, v242
	v_and_or_b32 v43, v243, s22, v16
	ds_write_b128 v80, v[36:39] offset:34816
	ds_write_b128 v80, v[40:43] offset:34960
	s_cbranch_scc1 .LBB0_356
	s_cmp_ge_i32 s80, s19
	s_mov_b64 s[74:75], -1
	s_cbranch_scc0 .LBB0_351
	s_sub_i32 s22, s80, s19
	s_mul_i32 s22, s22, s13
	s_add_i32 s76, s22, s62
	s_ashr_i32 s22, s76, 2
	s_and_b32 s22, s22, -8
	s_add_i32 s93, s22, 0x4080
	s_mov_b64 s[74:75], 0
